# static priority raise (s_setprio 1) for waves 4-7 over the whole prompt-attention unit
# baseline (speedup 1.0000x reference)
; __device__ __forceinline__ int otid() { int t = threadIdx.x; asm volatile("" : "+v"(t)); return t; }
; __device__ __forceinline__ void fox_prompt_unit(const Params& p, int b, int h, int qb, unsigned char* lds) {
;     const int tid = otid(), lane = tid & 63, r32 = lane & 31, hi = lane >> 5, wid = __builtin_amdgcn_readfirstlane(tid >> 6);
;     const bf16_t* P = (const bf16_t*)(p.ws + WS_P); const float* CKB = (const float*)(p.ws + WS_CKP) + (size_t)(b * 8 + h) * 4096; bf16_t* OB = (bf16_t*)(p.ws + WS_O) + (size_t)MT * 512;
;     bf16_t* Vt = (bf16_t*)lds;
;     const size_t rowbase = (size_t)b * 4096; const int q0 = qb * 256, qw0 = q0 + 32 * wid, myq = qw0 + r32;
;     const bf16_t* Qrow = P + (rowbase + myq) * NP + PC_FQ + h * 64;
;     bf16x8 qr[4];
; #pragma unroll
;     for (int d0 = 0; d0 < 4; ++d0) qr[d0] = *(const bf16x8*)(Qrow + d0 * 16 + hi * 8);
;     const bf16_t* Kg = P + rowbase * NP + PC_FK + h * 64;
;     const bf16_t* Vb = P + rowbase * NP + PC_FV + h * 64;
;     bf16_t* Kt = (bf16_t*)(lds + 19456);
;     const int vkey = tid >> 3, vdc = tid & 7;
;     f32x16 o0 = {}, o1 = {};
;     float mrun = -INFINITY, lrun = 0.f;
;     const int ntiles = (q0 + 256) / 64;
;     u32x4 vreg = *(const u32x4*)(Vb + (size_t)vkey * NP + vdc * 8);
;     float* sBias = (float*)(lds + 18944);
;     float breg = tid < 64 ? CKB[tid] : 0.f;
;     u32x4 kreg = *(const u32x4*)(Kg + (size_t)vkey * NP + vdc * 8);
; #pragma unroll
;     for (int j = 0; j < 8; ++j) Vt[(vdc * 8 + j) * 72 + vkey] = (bf16_t)((vreg[j >> 1] >> (16 * (j & 1))) & 0xffffu);
;     if (tid < 64) sBias[tid] = -breg * LOG2E;
;     *(u32x4*)(Kt + vkey * 72 + vdc * 8) = kreg;
;     if (1 < ntiles) { vreg = *(const u32x4*)(Vb + (size_t)(64 + vkey) * NP + vdc * 8); kreg = *(const u32x4*)(Kg + (size_t)(64 + vkey) * NP + vdc * 8); if (tid < 64) breg = CKB[64 + tid]; }
.LBB0_920:
	s_bfe_u32 s4, s57, 0x20003
	s_and_b32 s8, s57, 7
	s_lshl_b32 s0, s8, 14
	s_lshl_b32 s1, s4, 17
	v_mov_b32_e32 v90, v190
	s_or_b32 s0, s1, s0
	v_readlane_b32 s1, v255, 42
	s_add_u32 s0, s1, s0
	v_readfirstlane_b32 s2, v90
	v_readlane_b32 s1, v255, 43
	s_addc_u32 s1, s1, 0
	s_lshl_b32 s3, s57, 3
	s_ashr_i32 s2, s2, 1
	s_and_b32 s11, s3, 0x1f00
	s_andn2_b32 s2, s2, 31
	s_sub_i32 s10, s2, s11
	s_cmp_ge_u32 s2, 0x80
	s_cbranch_scc0 .Lfp_prio_skip
	s_setprio 1
.Lfp_prio_skip:
	s_waitcnt vmcnt(2)
	v_and_b32_e32 v13, 31, v90
	s_addk_i32 s10, 0x1300
	v_or_b32_e32 v94, s10, v13
	s_lshl_b32 s70, s4, 12
	v_ashrrev_i32_e32 v95, 31, v94
	v_readlane_b32 s6, v255, 34
	v_lshl_add_u64 v[92:93], v[94:95], 0, s[70:71]
	v_readlane_b32 s7, v255, 35
	s_lshl_b32 s70, s8, 7
	s_mul_i32 s4, s4, 0x2c00000
	s_waitcnt vmcnt(0)
	v_mov_b64_e32 v[2:3], s[6:7]
	s_add_u32 s9, s6, s4
	v_mad_u64_u32 v[2:3], s[2:3], v92, s33, v[2:3]
	s_addc_u32 s12, s7, 0
	v_bfe_u32 v12, v90, 5, 1
	v_mad_i32_i24 v3, v93, s33, v3
	s_add_u32 s2, s9, s70
	v_lshl_add_u64 v[2:3], v[2:3], 0, s[70:71]
	v_lshlrev_b32_e32 v10, 4, v12
	v_mov_b32_e32 v11, v1
	s_addc_u32 s3, s12, 0
	v_lshl_add_u64 v[2:3], v[2:3], 0, v[10:11]
	s_add_u32 s4, s2, 0x1600
	v_ashrrev_i32_e32 v11, 3, v90
	s_movk_i32 s2, 0x1600
	v_lshlrev_b32_e32 v0, 3, v90
	s_addc_u32 s5, s3, 0
	v_mad_i64_i32 v[6:7], s[2:3], v11, s2, 0
	v_and_b32_e32 v14, 56, v0
	global_load_dwordx4 v[66:69], v[2:3], off offset:3584
	global_load_dwordx4 v[70:73], v[2:3], off offset:3616
	global_load_dwordx4 v[74:77], v[2:3], off offset:3648
	global_load_dwordx4 v[78:81], v[2:3], off offset:3680
	v_lshl_add_u64 v[2:3], v[6:7], 1, s[4:5]
	v_lshlrev_b32_e32 v0, 1, v14
	v_lshl_add_u64 v[2:3], v[2:3], 0, v[0:1]
	global_load_dwordx4 v[2:5], v[2:3], off
	v_cmp_lt_i32_e32 vcc, 63, v90
	v_cmp_gt_i32_e64 s[2:3], 64, v90
	v_mov_b32_e32 v95, 0
	v_ashrrev_i32_e32 v91, 31, v90
	s_and_saveexec_b64 s[6:7], s[2:3]
	s_cbranch_execz .LBB0_922
	v_lshl_add_u64 v[8:9], v[90:91], 2, s[0:1]
	global_load_dword v95, v[8:9], off

; __device__ __forceinline__ unsigned pk2(float lo, float hi) { f32x2v v = {lo, hi}; hwbf16x2 b = __builtin_convertvector(v, hwbf16x2); return __builtin_bit_cast(unsigned, b); }
; __device__ __forceinline__ float shx(float x, int mask, int lane) { return __builtin_bit_cast(float, __builtin_amdgcn_ds_bpermute((lane ^ mask) << 2, __builtin_bit_cast(int, x))); }
; __device__ __forceinline__ void fox_prompt_unit(const Params& p, int b, int h, int qb, unsigned char* lds) {
;     ...
;     lrun += shx(lrun, 32, lane);
;     const float il = 1.0f / lrun;
;     bf16_t* Orow = OB + (rowbase + myq) * 512 + h * 64;
; #pragma unroll
;     for (int g = 0; g < 4; ++g) {
;         *(u32x2*)(Orow + 8 * g + 4 * hi) = (u32x2){pk2(o0[4 * g] * il, o0[4 * g + 1] * il), pk2(o0[4 * g + 2] * il, o0[4 * g + 3] * il)};
;         *(u32x2*)(Orow + 32 + 8 * g + 4 * hi) = (u32x2){pk2(o1[4 * g] * il, o1[4 * g + 1] * il), pk2(o1[4 * g + 2] * il, o1[4 * g + 3] * il)};
;     }
;     __syncthreads();
.LBB0_944:
	ds_bpermute_b32 v0, v107, v111
	v_readlane_b32 s0, v255, 40
	v_lshlrev_b64 v[34:35], 10, v[92:93]
	v_readlane_b32 s1, v255, 41
	s_waitcnt lgkmcnt(0)
	v_add_f32_e32 v0, v111, v0
	v_lshl_add_u64 v[34:35], s[0:1], 0, v[34:35]
	v_div_scale_f32 v36, s[0:1], v0, v0, 1.0
	v_rcp_f32_e32 v37, v36
	v_div_scale_f32 v38, vcc, 1.0, v0, 1.0
	v_lshl_add_u64 v[34:35], v[34:35], 0, s[70:71]
	v_fma_f32 v39, -v36, v37, 1.0
	v_fmac_f32_e32 v37, v39, v37
	v_mul_f32_e32 v39, v38, v37
	v_fma_f32 v40, -v36, v39, v38
	v_fmac_f32_e32 v39, v40, v37
	v_fma_f32 v36, -v36, v39, v38
	v_div_fmas_f32 v36, v36, v37, v39
	v_div_fixup_f32 v36, v36, v0, 1.0
	v_lshlrev_b32_e32 v0, 1, v105
	v_pk_mul_f32 v[2:3], v[2:3], v[36:37] op_sel_hi:[1,0]
	v_pk_mul_f32 v[4:5], v[4:5], v[36:37] op_sel_hi:[1,0]
	v_lshl_add_u64 v[34:35], v[34:35], 0, v[0:1]
	v_cvt_pk_bf16_f32 v2, v2, v3
	v_cvt_pk_bf16_f32 v3, v4, v5
	global_store_dwordx2 v[34:35], v[2:3], off offset:64
	v_pk_mul_f32 v[2:3], v[22:23], v[36:37] op_sel_hi:[1,0]
	v_pk_mul_f32 v[4:5], v[24:25], v[36:37] op_sel_hi:[1,0]
	v_cvt_pk_bf16_f32 v2, v2, v3
	v_cvt_pk_bf16_f32 v3, v4, v5
	global_store_dwordx2 v[34:35], v[2:3], off offset:16
	v_pk_mul_f32 v[2:3], v[6:7], v[36:37] op_sel_hi:[1,0]
	v_pk_mul_f32 v[4:5], v[8:9], v[36:37] op_sel_hi:[1,0]
	v_cvt_pk_bf16_f32 v2, v2, v3
	v_cvt_pk_bf16_f32 v3, v4, v5
	global_store_dwordx2 v[34:35], v[2:3], off offset:80
	v_pk_mul_f32 v[2:3], v[26:27], v[36:37] op_sel_hi:[1,0]
	v_pk_mul_f32 v[4:5], v[28:29], v[36:37] op_sel_hi:[1,0]
	v_cvt_pk_bf16_f32 v2, v2, v3
	v_cvt_pk_bf16_f32 v3, v4, v5
	global_store_dwordx2 v[34:35], v[2:3], off offset:32
	v_pk_mul_f32 v[2:3], v[10:11], v[36:37] op_sel_hi:[1,0]
	v_pk_mul_f32 v[4:5], v[12:13], v[36:37] op_sel_hi:[1,0]
	v_cvt_pk_bf16_f32 v2, v2, v3
	v_cvt_pk_bf16_f32 v3, v4, v5
	global_store_dwordx2 v[34:35], v[2:3], off offset:96
	v_pk_mul_f32 v[2:3], v[30:31], v[36:37] op_sel_hi:[1,0]
	v_pk_mul_f32 v[4:5], v[32:33], v[36:37] op_sel_hi:[1,0]
	v_cvt_pk_bf16_f32 v2, v2, v3
	v_cvt_pk_bf16_f32 v3, v4, v5
	v_pk_mul_f32 v[18:19], v[18:19], v[36:37] op_sel_hi:[1,0]
	v_pk_mul_f32 v[20:21], v[20:21], v[36:37] op_sel_hi:[1,0]
	global_store_dwordx2 v[34:35], v[2:3], off offset:48
	v_pk_mul_f32 v[2:3], v[14:15], v[36:37] op_sel_hi:[1,0]
	v_pk_mul_f32 v[4:5], v[16:17], v[36:37] op_sel_hi:[1,0]
	v_cvt_pk_bf16_f32 v18, v18, v19
	v_cvt_pk_bf16_f32 v19, v20, v21
	v_cvt_pk_bf16_f32 v2, v2, v3
	v_cvt_pk_bf16_f32 v3, v4, v5
	global_store_dwordx2 v[34:35], v[18:19], off
	global_store_dwordx2 v[34:35], v[2:3], off offset:112
	s_setprio 0
	s_barrier
